# P13 chunk loop: top-of-iteration waits count the 16 Y2 stores issued after the prefetched operand loads (vmcnt(16..25) instead of vmcnt(0/1)); loop entered with vmcnt(0)
# baseline (speedup 1.0000x reference)
.LBB0_2664:
	s_or_b64 exec, exec, s[6:7]
	s_waitcnt vmcnt(11)
	v_mul_f32_e32 v8, 0x3fb8aa3b, v8
	v_exp_f32_e32 v152, v8
	v_mul_u32_u24_e32 v8, 0x88, v4
	v_and_b32_e32 v150, 31, v1
	v_lshlrev_b32_e32 v14, 1, v8
	v_lshlrev_b32_e32 v8, 2, v4
	v_and_b32_e32 v16, 0xe0, v4
	v_add_u32_e32 v154, 0x11900, v8
	v_add_u32_e32 v155, 0x11800, v8
	v_or_b32_e32 v8, v16, v150
	v_bfe_u32 v12, v1, 5, 1
	v_mul_u32_u24_e32 v9, 0x110, v8
	v_lshlrev_b32_e32 v8, 7, v8
	s_add_u32 s2, s4, s2
	v_lshlrev_b32_e32 v18, 4, v12
	v_sub_u32_e32 v8, v9, v8
	v_readlane_b32 s12, v244, 14
	s_addc_u32 s3, s5, 0
	v_add_u32_e32 v158, v8, v18
	v_lshrrev_b32_e32 v8, 1, v1
	s_lshl_b32 s88, s8, 1
	v_readlane_b32 s26, v244, 28
	v_lshlrev_b32_e32 v156, 3, v12
	v_and_b32_e32 v8, 32, v8
	v_readlane_b32 s27, v244, 29
	s_add_u32 s6, s26, s88
	v_mov_b32_e32 v140, 0
	v_or_b32_e32 v157, v9, v156
	v_and_b32_e32 v10, 0x380, v1
	v_or_b32_e32 v19, v8, v150
	s_addc_u32 s7, s27, 0
	v_lshlrev_b32_e32 v8, 1, v8
	v_mov_b32_e32 v9, v140
	v_or_b32_e32 v17, 0x11800, v10
	v_lshl_add_u64 v[8:9], s[6:7], 0, v[8:9]
	v_lshlrev_b32_e32 v10, 1, v150
	v_mov_b32_e32 v11, v140
	v_and_b32_e32 v3, 63, v1
	v_lshl_add_u64 v[8:9], v[8:9], 0, v[10:11]
	s_mov_b64 s[6:7], 0x16b00000
	v_lshl_add_u64 v[142:143], v[8:9], 0, s[6:7]
	v_lshlrev_b32_e32 v8, 2, v3
	s_movk_i32 s10, 0x90
	v_or_b32_e32 v160, 0x11800, v8
	v_or_b32_e32 v161, 0x11900, v8
	v_lshlrev_b32_e32 v8, 7, v19
	s_movk_i32 s9, 0xfef2
	v_readlane_b32 s13, v244, 15
	v_readlane_b32 s14, v244, 16
	v_readlane_b32 s15, v244, 17
	v_readlane_b32 s16, v244, 18
	v_readlane_b32 s17, v244, 19
	v_mad_u32_u24 v8, v19, s10, v8
	v_mad_i32_i24 v15, v4, s9, v14
	v_mad_u32_u24 v159, v19, s10, v18
	v_add_u32_e32 v162, v8, v18
	v_lshlrev_b32_e32 v9, 2, v19
	v_mad_i32_i24 v8, v19, s9, v8
	v_cmp_eq_u32_e64 s[6:7], 0, v3
	v_cmp_gt_u32_e64 s[8:9], 2, v3
	v_cmp_gt_u32_e64 s[10:11], 4, v3
	v_cmp_gt_u32_e64 s[12:13], 8, v3
	v_cmp_gt_u32_e64 s[14:15], 16, v3
	v_cmp_gt_u32_e64 s[16:17], 32, v3
	v_mul_u32_u24_e32 v3, 0x900, v7
	v_or_b32_e32 v13, 8, v138
	v_or_b32_e32 v163, 0x11800, v9
	v_or_b32_e32 v164, 0x11900, v9
	v_lshlrev_b32_e32 v3, 1, v3
	v_lshlrev_b32_e32 v9, 1, v4
	v_add_u32_e32 v166, v15, v3
	v_add_u32_e32 v167, v3, v9
	v_mul_u32_u24_e32 v3, 0x48, v13
	v_lshlrev_b32_e32 v3, 1, v3
	v_lshlrev_b32_e32 v153, 2, v12
	v_add_u32_e32 v168, v15, v3
	v_add_u32_e32 v169, v3, v9
	v_add_u32_e32 v11, 0x480, v3
	v_add_u32_e32 v3, 0x900, v3
	v_or_b32_e32 v20, v153, v16
	v_add_u32_e32 v172, v15, v3
	v_add_u32_e32 v173, v3, v9
	v_mul_u32_u24_e32 v3, 0x480, v7
	v_readlane_b32 s22, v244, 24
	v_readlane_b32 s23, v244, 25
	v_readlane_b32 s24, v244, 26
	v_readlane_b32 s25, v244, 27
	v_add_u32_e32 v171, v11, v9
	v_lshl_add_u32 v174, v3, 1, v15
	v_mov_b32_e32 v3, 0x11800
	v_or_b32_e32 v9, 1, v20
	v_cmp_le_u32_e64 s[22:23], v19, v9
	v_lshl_or_b32 v176, v9, 2, v3
	v_cmp_eq_u32_e64 s[24:25], v19, v9
	v_or_b32_e32 v9, 2, v20
	v_cmp_le_u32_e64 s[26:27], v19, v9
	v_lshl_or_b32 v177, v9, 2, v3
	v_cmp_eq_u32_e64 s[28:29], v19, v9
	v_or_b32_e32 v9, 3, v20
	v_cmp_le_u32_e64 s[30:31], v19, v9
	v_lshl_or_b32 v178, v9, 2, v3
	v_cmp_eq_u32_e64 s[34:35], v19, v9
	v_or_b32_e32 v9, 8, v20
	v_cmp_le_u32_e64 s[36:37], v19, v9
	v_lshl_or_b32 v179, v9, 2, v3
	v_cmp_eq_u32_e64 s[38:39], v19, v9
	v_or_b32_e32 v9, 9, v20
	v_cmp_le_u32_e64 s[40:41], v19, v9
	v_lshl_or_b32 v180, v9, 2, v3
	v_cmp_eq_u32_e64 s[42:43], v19, v9
	v_or_b32_e32 v9, 10, v20
	v_readlane_b32 s18, v244, 20
	v_readlane_b32 s19, v244, 21
	v_readlane_b32 s20, v244, 22
	v_readlane_b32 s21, v244, 23
	v_cmp_le_u32_e64 s[44:45], v19, v9
	v_lshl_or_b32 v181, v9, 2, v3
	v_cmp_eq_u32_e64 s[46:47], v19, v9
	v_or_b32_e32 v9, 11, v20
	v_lshl_add_u32 v165, v138, 1, v14
	v_add_u32_e32 v170, v15, v11
	v_cmp_le_u32_e64 s[18:19], v19, v20
	v_lshl_or_b32 v175, v20, 2, v3
	v_cmp_eq_u32_e64 s[20:21], v19, v20
	v_mul_u32_u24_e32 v7, 0x90, v20
	v_cmp_le_u32_e64 s[48:49], v19, v9
	v_lshl_or_b32 v182, v9, 2, v3
	v_cmp_eq_u32_e64 s[50:51], v19, v9
	v_or_b32_e32 v9, 16, v20
	v_or_b32_e32 v11, 17, v20
	v_or_b32_e32 v13, 18, v20
	v_or_b32_e32 v14, 19, v20
	v_or_b32_e32 v15, 24, v20
	v_or_b32_e32 v21, 25, v20
	v_or_b32_e32 v22, 26, v20
	v_or_b32_e32 v20, 27, v20
	v_lshl_or_b32 v183, v9, 2, v3
	v_lshl_or_b32 v184, v11, 2, v3
	v_lshl_or_b32 v185, v13, 2, v3
	v_lshl_or_b32 v186, v14, 2, v3
	v_lshl_or_b32 v187, v15, 2, v3
	v_lshl_or_b32 v188, v21, 2, v3
	v_lshl_or_b32 v189, v22, 2, v3
	v_lshl_or_b32 v190, v20, 2, v3
	v_mul_u32_u24_e32 v3, 0x240, v12
	v_add_u32_e32 v202, 64, v2
	v_lshrrev_b32_e32 v151, 6, v1
	v_or_b32_e32 v191, v3, v10
	v_mul_u32_u24_e32 v3, 0x90, v150
	v_mbcnt_lo_u32_b32 v2, -1, 0
	v_cmp_ne_u32_e64 s[4:5], 1, v151
	v_cmp_le_u32_e64 s[52:53], v19, v9
	v_cmp_eq_u32_e64 s[54:55], v19, v9
	v_cmp_le_u32_e64 s[56:57], v19, v11
	v_cmp_eq_u32_e64 s[58:59], v19, v11
	v_cmp_le_u32_e64 s[60:61], v19, v13
	v_cmp_eq_u32_e64 s[62:63], v19, v13
	v_cmp_le_u32_e64 s[64:65], v19, v14
	v_cmp_eq_u32_e64 s[66:67], v19, v14
	v_cmp_le_u32_e64 s[68:69], v19, v15
	v_cmp_eq_u32_e64 s[70:71], v19, v15
	v_cmp_le_u32_e64 s[72:73], v19, v21
	v_cmp_eq_u32_e64 s[74:75], v19, v21
	v_cmp_le_u32_e64 s[76:77], v19, v22
	v_cmp_eq_u32_e64 s[78:79], v19, v22
	v_cmp_le_u32_e64 s[80:81], v19, v20
	v_cmp_eq_u32_e64 s[82:83], v19, v20
	s_movk_i32 s33, 0x810
	v_sub_u32_e32 v192, 0x810, v16
	v_sub_u32_e32 v193, 0x810, v9
	v_sub_u32_e32 v194, 0x810, v11
	v_sub_u32_e32 v195, 0x810, v13
	v_sub_u32_e32 v196, 0x810, v14
	v_sub_u32_e32 v197, 0x810, v15
	v_sub_u32_e32 v198, 0x810, v21
	v_sub_u32_e32 v199, 0x810, v22
	v_sub_u32_e32 v200, 0x810, v20
	v_add3_u32 v201, s89, v16, v153
	v_add_u32_e32 v203, 64, v5
	v_add_u32_e32 v204, 64, v4
	v_mov_b32_e32 v205, 0x3ecc95a3
	v_mov_b32_e32 v206, 0x118fc
	v_lshlrev_b32_e32 v144, 1, v6
	v_add_u32_e32 v207, v17, v18
	v_add_u32_e32 v208, v18, v3
	v_mov_b32_e32 v146, 0x3f317218
	v_mov_b32_e32 v209, 0x7f800000
	v_mov_b32_e32 v210, 0x7fc00000
	v_mov_b32_e32 v211, 0xff800000
	v_mbcnt_hi_u32_b32 v212, -1, v2
	v_add_u32_e32 v213, v8, v7
	s_mov_b32 s96, s85
	v_mov_b32_e32 v2, 0
	v_mov_b32_e32 v3, v140
	v_mov_b32_e32 v4, v140
	v_mov_b32_e32 v5, v140
	v_mov_b32_e32 v6, v140
	v_mov_b32_e32 v7, v140
	v_mov_b32_e32 v8, v140
	v_mov_b32_e32 v9, v140
	v_mov_b32_e32 v10, v140
	v_mov_b32_e32 v11, v140
	v_mov_b32_e32 v12, v140
	v_mov_b32_e32 v13, v140
	v_mov_b32_e32 v14, v140
	v_mov_b32_e32 v15, v140
	v_mov_b32_e32 v16, v140
	v_mov_b32_e32 v17, v140
	v_mov_b32_e32 v18, 0
	v_mov_b32_e32 v19, v140
	v_mov_b32_e32 v20, v140
	v_mov_b32_e32 v21, v140
	v_mov_b32_e32 v22, v140
	v_mov_b32_e32 v23, v140
	v_mov_b32_e32 v24, v140
	v_mov_b32_e32 v25, v140
	v_mov_b32_e32 v26, v140
	v_mov_b32_e32 v27, v140
	v_mov_b32_e32 v28, v140
	v_mov_b32_e32 v29, v140
	v_mov_b32_e32 v30, v140
	v_mov_b32_e32 v31, v140
	v_mov_b32_e32 v32, v140
	v_mov_b32_e32 v33, v140
	v_mov_b32_e32 v34, 0
	v_mov_b32_e32 v35, v140
	v_mov_b32_e32 v36, v140
	v_mov_b32_e32 v37, v140
	v_mov_b32_e32 v38, v140
	v_mov_b32_e32 v39, v140
	v_mov_b32_e32 v40, v140
	v_mov_b32_e32 v41, v140
	v_mov_b32_e32 v42, v140
	v_mov_b32_e32 v43, v140
	v_mov_b32_e32 v44, v140
	v_mov_b32_e32 v45, v140
	v_mov_b32_e32 v46, v140
	v_mov_b32_e32 v47, v140
	v_mov_b32_e32 v48, v140
	v_mov_b32_e32 v49, v140
	v_mov_b32_e32 v50, 0
	v_mov_b32_e32 v51, v140
	v_mov_b32_e32 v52, v140
	v_mov_b32_e32 v53, v140
	v_mov_b32_e32 v54, v140
	v_mov_b32_e32 v55, v140
	v_mov_b32_e32 v56, v140
	v_mov_b32_e32 v57, v140
	v_mov_b32_e32 v58, v140
	v_mov_b32_e32 v59, v140
	v_mov_b32_e32 v60, v140
	v_mov_b32_e32 v61, v140
	v_mov_b32_e32 v62, v140
	v_mov_b32_e32 v63, v140
	v_mov_b32_e32 v64, v140
	v_mov_b32_e32 v65, v140
	s_waitcnt vmcnt(0)
	s_branch .LBB0_2666

.LBB0_2666:
	s_and_saveexec_b64 s[90:91], s[0:1]
	s_cbranch_execz .LBB0_2670
	v_add_u32_e32 v66, s96, v1
	v_cmp_gt_u32_e32 vcc, s33, v66
	v_mov_b32_e32 v66, 0
	s_and_saveexec_b64 s[92:93], vcc
	s_cbranch_execz .LBB0_2669
	s_waitcnt vmcnt(16)
	v_add_f32_e32 v66, v148, v139
	s_mov_b32 s89, 0xbfb8aa3b
	v_mul_f32_e64 v67, |v66|, s89
	v_exp_f32_e32 v80, v67
	v_max_f32_e32 v81, 0, v66
	s_mov_b32 s89, 0x3f2aaaab
	v_add_f32_e32 v68, 1.0, v80
	v_add_f32_e32 v66, -1.0, v68
	v_sub_f32_e32 v67, v66, v68
	v_sub_f32_e32 v66, v80, v66
	v_add_f32_e32 v67, 1.0, v67
	v_frexp_mant_f32_e32 v69, v68
	v_add_f32_e32 v70, v66, v67
	v_cvt_f64_f32_e32 v[66:67], v68
	v_frexp_exp_i32_f64_e32 v66, v[66:67]
	v_cmp_gt_f32_e32 vcc, s89, v69
	s_mov_b32 s89, 0x3f317218
	s_nop 0
	v_subbrev_co_u32_e32 v74, vcc, 0, v66, vcc
	v_sub_u32_e32 v66, 0, v74
	v_ldexp_f32 v67, v68, v66
	v_ldexp_f32 v66, v70, v66
	v_add_f32_e32 v68, -1.0, v67
	v_add_f32_e32 v70, 1.0, v67
	v_add_f32_e32 v69, 1.0, v68
	v_add_f32_e32 v71, -1.0, v70
	v_sub_f32_e32 v69, v67, v69
	v_sub_f32_e32 v67, v67, v71
	v_add_f32_e32 v69, v66, v69
	v_add_f32_e32 v66, v66, v67
	v_add_f32_e32 v75, v70, v66
	v_rcp_f32_e32 v77, v75
	v_sub_f32_e32 v67, v75, v70
	v_sub_f32_e32 v76, v66, v67
	v_add_f32_e32 v67, v68, v69
	v_mul_f32_e32 v79, v67, v77
	v_sub_f32_e32 v66, v67, v68
	v_mul_f32_e32 v68, v75, v79
	v_fma_f32 v70, v79, v75, -v68
	v_fmac_f32_e32 v70, v79, v76
	v_sub_f32_e32 v78, v69, v66
	v_add_f32_e32 v66, v68, v70
	v_sub_f32_e32 v69, v67, v66
	v_pk_add_f32 v[72:73], v[66:67], v[68:69] neg_lo:[0,1] neg_hi:[0,1]
	v_mov_b32_e32 v71, v66
	v_pk_add_f32 v[66:67], v[72:73], v[70:71] neg_lo:[0,1] neg_hi:[0,1]
	s_nop 0
	v_add_f32_e32 v67, v78, v67
	v_add_f32_e32 v66, v66, v67
	v_add_f32_e32 v67, v69, v66
	v_mul_f32_e32 v78, v77, v67
	v_mul_f32_e32 v68, v75, v78
	v_fma_f32 v70, v78, v75, -v68
	v_fmac_f32_e32 v70, v78, v76
	v_sub_f32_e32 v69, v69, v67
	v_add_f32_e32 v75, v66, v69
	v_add_f32_e32 v66, v68, v70
	v_sub_f32_e32 v69, v67, v66
	v_pk_add_f32 v[72:73], v[66:67], v[68:69] neg_lo:[0,1] neg_hi:[0,1]
	v_mov_b32_e32 v71, v66
	v_pk_add_f32 v[66:67], v[72:73], v[70:71] neg_lo:[0,1] neg_hi:[0,1]
	s_nop 0
	v_add_f32_e32 v67, v75, v67
	v_add_f32_e32 v66, v66, v67
	v_add_f32_e32 v67, v79, v78
	v_add_f32_e32 v66, v69, v66
	v_sub_f32_e32 v68, v67, v79
	v_mul_f32_e32 v66, v77, v66
	v_sub_f32_e32 v68, v78, v68
	v_add_f32_e32 v68, v68, v66
	v_add_f32_e32 v70, v67, v68
	v_mul_f32_e32 v71, v70, v70
	v_fmamk_f32 v66, v71, 0x3e9b6dac, v205
	v_fmaak_f32 v147, v71, v66, 0x3f2aaada
	v_cvt_f32_i32_e32 v66, v74
	v_sub_f32_e32 v67, v70, v67
	v_sub_f32_e32 v67, v68, v67
	v_ldexp_f32 v72, v67, 1
	v_mul_f32_e32 v67, v70, v71
	v_ldexp_f32 v69, v70, 1
	v_pk_mul_f32 v[70:71], v[66:67], v[146:147]
	s_nop 0
	v_fma_f32 v68, v66, s89, -v70
	v_fmac_f32_e32 v68, 0xb102e308, v66
	v_pk_add_f32 v[66:67], v[70:71], v[68:69]
	s_mov_b32 s89, 0x7f800000
	v_sub_f32_e32 v69, v67, v69
	v_sub_f32_e32 v69, v71, v69
	v_add_f32_e32 v73, v72, v69
	v_mov_b32_e32 v72, v70
	v_pk_add_f32 v[70:71], v[66:67], v[70:71] neg_lo:[0,1] neg_hi:[0,1]
	v_pk_add_f32 v[74:75], v[66:67], v[72:73]
	v_mov_b32_e32 v69, v66
	v_mov_b32_e32 v71, v75
	v_pk_add_f32 v[76:77], v[68:69], v[70:71] neg_lo:[0,1] neg_hi:[0,1]
	v_pk_add_f32 v[68:69], v[68:69], v[70:71]
	v_mov_b32_e32 v72, v73
	v_pk_add_f32 v[70:71], v[68:69], v[66:67] op_sel:[1,0] op_sel_hi:[0,1] neg_lo:[0,1] neg_hi:[0,1]
	v_pk_add_f32 v[78:79], v[74:75], v[70:71] op_sel_hi:[1,0] neg_lo:[0,1] neg_hi:[0,1]
	v_mov_b32_e32 v74, v75
	v_mov_b32_e32 v75, v69
	v_pk_mov_b32 v[70:71], v[66:67], v[70:71] op_sel:[1,0]
	v_mov_b32_e32 v73, v66
	v_pk_add_f32 v[70:71], v[74:75], v[70:71] neg_lo:[0,1] neg_hi:[0,1]
	v_mov_b32_e32 v78, v76
	v_pk_add_f32 v[66:67], v[72:73], v[70:71] neg_lo:[0,1] neg_hi:[0,1]
	v_mov_b32_e32 v77, v69
	v_pk_add_f32 v[70:71], v[78:79], v[66:67]
	v_cmp_neq_f32_e32 vcc, s89, v80
	v_pk_add_f32 v[72:73], v[70:71], v[70:71] op_sel:[0,1] op_sel_hi:[1,0]
	s_mov_b32 s89, 0x33800000
	v_pk_add_f32 v[68:69], v[68:69], v[72:73] op_sel:[1,0] op_sel_hi:[0,1]
	v_mov_b32_e32 v71, v68
	v_pk_add_f32 v[74:75], v[70:71], v[76:77] neg_lo:[0,1] neg_hi:[0,1]
	v_mov_b32_e32 v67, v72
	v_sub_f32_e32 v69, v70, v74
	v_pk_add_f32 v[66:67], v[66:67], v[74:75] neg_lo:[0,1] neg_hi:[0,1]
	v_sub_f32_e32 v69, v76, v69
	v_add_f32_e32 v66, v66, v69
	v_add_f32_e32 v66, v66, v67
	v_add_f32_e32 v66, v68, v66
	v_cndmask_b32_e32 v66, v209, v66, vcc
	v_cmp_ngt_f32_e32 vcc, -1.0, v80
	s_nop 1
	v_cndmask_b32_e32 v66, v210, v66, vcc
	v_cmp_neq_f32_e32 vcc, -1.0, v80
	s_nop 1
	v_cndmask_b32_e32 v66, v211, v66, vcc
	v_cmp_lt_f32_e64 vcc, |v80|, s89
	s_nop 1
	v_cndmask_b32_e32 v66, v66, v80, vcc
	v_add_f32_e32 v66, v81, v66

.LBB0_2670:
	s_or_b64 exec, exec, s[90:91]
	s_waitcnt vmcnt(25)
	ds_write_b128 v165, v[102:105]
	s_waitcnt vmcnt(23)
	ds_write_b128 v165, v[106:109] offset:17408
	ds_write_b16 v166, v106 offset:34816
	ds_write_b16_d16_hi v167, v106 offset:34960
	ds_write_b16 v166, v107 offset:35104
	ds_write_b16_d16_hi v167, v107 offset:35248
	ds_write_b16 v166, v108 offset:35392
	ds_write_b16_d16_hi v167, v108 offset:35536
	ds_write_b16 v166, v109 offset:35680
	ds_write_b16_d16_hi v167, v109 offset:35824
	ds_write_b128 v165, v[98:101] offset:16
	s_waitcnt vmcnt(21)
	ds_write_b128 v165, v[110:113] offset:17424
	ds_write_b16 v168, v110 offset:34816
	ds_write_b16_d16_hi v169, v110 offset:34960
	ds_write_b16 v166, v111 offset:36256
	ds_write_b16_d16_hi v167, v111 offset:36400
	ds_write_b16 v166, v112 offset:36544
	ds_write_b16_d16_hi v167, v112 offset:36688
	ds_write_b16 v166, v113 offset:36832
	ds_write_b16_d16_hi v167, v113 offset:36976
	ds_write_b128 v165, v[114:117] offset:32
	s_waitcnt vmcnt(19)
	ds_write_b128 v165, v[118:121] offset:17440
	ds_write_b16 v170, v118 offset:34816
	ds_write_b16_d16_hi v171, v118 offset:34960
	ds_write_b16 v166, v119 offset:37408
	ds_write_b16_d16_hi v167, v119 offset:37552
	ds_write_b16 v166, v120 offset:37696
	ds_write_b16_d16_hi v167, v120 offset:37840
	ds_write_b16 v166, v121 offset:37984
	ds_write_b16_d16_hi v167, v121 offset:38128
	ds_write_b128 v165, v[122:125] offset:48
	s_waitcnt vmcnt(18)
	ds_write_b128 v165, v[126:129] offset:17456
	ds_write_b16 v172, v126 offset:34816
	ds_write_b16_d16_hi v173, v126 offset:34960
	ds_write_b16 v166, v127 offset:38560
	ds_write_b16_d16_hi v167, v127 offset:38704
	ds_write_b16 v166, v128 offset:38848
	ds_write_b16_d16_hi v167, v128 offset:38992
	ds_write_b16 v166, v129 offset:39136
	ds_write_b16_d16_hi v167, v129 offset:39280
	s_waitcnt lgkmcnt(0)
	s_barrier
	ds_read_b32 v66, v206
	ds_read_b32 v67, v155
	ds_read_b32 v68, v154
	s_waitcnt vmcnt(16)
	v_and_b32_e32 v69, 0xffff0000, v134
	ds_write_b16 v174, v134 offset:53248
	ds_write_b16_d16_hi v174, v134 offset:53392
	s_cmpk_gt_u32 s96, 0x7cf
	s_waitcnt lgkmcnt(3)
	v_sub_f32_e32 v66, v66, v67
	v_mul_f32_e32 v66, 0x3fb8aa3b, v66
	v_exp_f32_e32 v66, v66
	s_cselect_b64 s[90:91], -1, 0
	s_and_b64 vcc, exec, s[90:91]
	s_waitcnt lgkmcnt(2)
	v_mul_f32_e32 v66, v68, v66
	v_lshlrev_b32_e32 v68, 16, v134
	v_pk_mul_f32 v[68:69], v[66:67], v[68:69] op_sel_hi:[0,1]
	v_cvt_pk_bf16_f32 v67, v68, v69
	v_lshlrev_b32_e32 v68, 16, v135
	v_and_b32_e32 v69, 0xffff0000, v135
	v_pk_mul_f32 v[68:69], v[66:67], v[68:69] op_sel_hi:[0,1]
	ds_write_b16 v174, v67 offset:62464
	ds_write_b16_d16_hi v174, v67 offset:62608
	ds_write_b16 v174, v135 offset:53536
	ds_write_b16_d16_hi v174, v135 offset:53680
	v_cvt_pk_bf16_f32 v67, v68, v69
	v_lshlrev_b32_e32 v68, 16, v136
	v_and_b32_e32 v69, 0xffff0000, v136
	v_pk_mul_f32 v[68:69], v[66:67], v[68:69] op_sel_hi:[0,1]
	ds_write_b16 v174, v67 offset:62752
	ds_write_b16_d16_hi v174, v67 offset:62896
	ds_write_b16 v174, v136 offset:53824
	ds_write_b16_d16_hi v174, v136 offset:53968
	v_cvt_pk_bf16_f32 v67, v68, v69
	v_lshlrev_b32_e32 v68, 16, v137
	v_and_b32_e32 v69, 0xffff0000, v137
	v_pk_mul_f32 v[68:69], v[66:67], v[68:69] op_sel_hi:[0,1]
	ds_write_b16 v174, v67 offset:63040
	ds_write_b16_d16_hi v174, v67 offset:63184
	ds_write_b16 v174, v137 offset:54112
	ds_write_b16_d16_hi v174, v137 offset:54256
	v_cvt_pk_bf16_f32 v67, v68, v69
	v_lshlrev_b32_e32 v68, 16, v130
	v_and_b32_e32 v69, 0xffff0000, v130
	v_pk_mul_f32 v[68:69], v[66:67], v[68:69] op_sel_hi:[0,1]
	ds_write_b16 v174, v67 offset:63328
	ds_write_b16_d16_hi v174, v67 offset:63472
	ds_write_b16 v174, v130 offset:54400
	ds_write_b16_d16_hi v174, v130 offset:54544
	v_cvt_pk_bf16_f32 v67, v68, v69
	v_lshlrev_b32_e32 v68, 16, v131
	v_and_b32_e32 v69, 0xffff0000, v131
	v_pk_mul_f32 v[68:69], v[66:67], v[68:69] op_sel_hi:[0,1]
	ds_write_b16 v174, v67 offset:63616
	ds_write_b16_d16_hi v174, v67 offset:63760
	ds_write_b16 v174, v131 offset:54688
	ds_write_b16_d16_hi v174, v131 offset:54832
	v_cvt_pk_bf16_f32 v67, v68, v69
	v_lshlrev_b32_e32 v68, 16, v132
	v_and_b32_e32 v69, 0xffff0000, v132
	v_pk_mul_f32 v[68:69], v[66:67], v[68:69] op_sel_hi:[0,1]
	ds_write_b16 v174, v67 offset:63904
	ds_write_b16_d16_hi v174, v67 offset:64048
	ds_write_b16 v174, v132 offset:54976
	ds_write_b16_d16_hi v174, v132 offset:55120
	v_cvt_pk_bf16_f32 v67, v68, v69
	v_lshlrev_b32_e32 v68, 16, v133
	v_and_b32_e32 v69, 0xffff0000, v133
	ds_write_b16 v174, v67 offset:64192
	ds_write_b16_d16_hi v174, v67 offset:64336
	ds_write_b16 v174, v133 offset:55264
	ds_write_b16_d16_hi v174, v133 offset:55408
	v_pk_mul_f32 v[66:67], v[66:67], v[68:69] op_sel_hi:[0,1]
	v_cvt_pk_bf16_f32 v66, v66, v67
	ds_write_b16 v174, v66 offset:64480
	ds_write_b16_d16_hi v174, v66 offset:64624
	s_cbranch_vccnz .LBB0_2686
	v_add_u32_e32 v66, s96, v204
	v_cmp_gt_u32_e32 vcc, s33, v66
	v_add_u32_e32 v68, s96, v203
	v_mov_b64_e32 v[66:67], s[86:87]
	s_movk_i32 s89, 0x1800
	v_mad_i64_i32 v[66:67], s[92:93], v68, s89, v[66:67]
	s_mov_b64 s[92:93], 0x1400
	s_nop 0
	v_lshl_add_u64 v[72:73], v[66:67], 0, s[92:93]
	s_mov_b64 s[92:93], 0x1000
	v_mov_b32_e32 v141, v140
	v_mov_b32_e32 v100, v140
	v_mov_b32_e32 v101, v140
	v_lshl_add_u64 v[68:69], v[66:67], 0, s[92:93]
	v_lshlrev_b32_e32 v70, 1, v138
	v_mov_b64_e32 v[104:105], v[100:101]
	v_mov_b64_e32 v[102:103], v[100:101]
	v_mov_b64_e32 v[108:109], v[140:141]
	v_mov_b64_e32 v[106:107], v[140:141]
	s_and_saveexec_b64 s[92:93], vcc
	s_cbranch_execz .LBB0_2673
	v_lshl_add_u64 v[74:75], v[72:73], 0, s[84:85]
	v_mov_b32_e32 v71, v140
	v_lshl_add_u64 v[74:75], v[74:75], 0, v[70:71]
	v_lshl_add_u64 v[76:77], v[68:69], 0, s[84:85]
	v_lshl_add_u64 v[76:77], v[76:77], 0, v[70:71]
	global_load_dwordx4 v[102:105], v[74:75], off
	global_load_dwordx4 v[106:109], v[76:77], off
